# lrumath: LRU gemm_tile epilogue hand-written (8 gate elements interleaved, branch-free expm1 select, parameter loads batched, compiler softplus slices replayed)
# speedup vs baseline: 1.0050x; 1.0050x over previous
; #define MFMA16(a, b, c) __builtin_amdgcn_mfma_f32_16x16x32_bf16(a, b, c, 0, 0, 0)
; template <int EPI>
; __device__ __forceinline__ void gemm_tile(const Params& p, const EpiArgs& ea, const bf16_t* __restrict__ A, int lda,
;                                           const bf16_t* __restrict__ Bt, int K, int m0, int n0, char* smem) {
;     ...
;     for (int ks = 0; ks < 2; ++ks) {
;       bf16x8 af[4], bfg[4];
; #pragma unroll
;       for (int mi = 0; mi < 4; ++mi) af[mi] = *(const bf16x8*)(cA + mi * 16 * LDT + ks * 32);
; #pragma unroll
;       for (int ni = 0; ni < 4; ++ni) bfg[ni] = *(const bf16x8*)(cB + ni * 16 * LDT + ks * 32);
; #pragma unroll
;       for (int mi = 0; mi < 4; ++mi)
; #pragma unroll
;         for (int ni = 0; ni < 4; ++ni) acc[mi][ni] = MFMA16(af[mi], bfg[ni], acc[mi][ni]);
;     }
;     ...
;       for (int nh = 0; nh < 2; ++nh) {
;         int ch = (n0 >> 1) + wn * 32 + nh * 16 + fr;
;         float ba = p.lru_b_a[ea.dir * 1024 + ch], bx = p.lru_b_x[ea.dir * 1024 + ch];
;         float sp8 = -8.0f * log1pf(__expf(-p.lru_lam[ea.dir * 1024 + ch]));
.Llru_pf_skip1:
	ds_read_b128 v[0:3], v114 offset:36864
	ds_read_b128 v[4:7], v114 offset:39168
	ds_read_b128 v[8:11], v114 offset:41472
	ds_read_b128 v[80:83], v114 offset:43776
	ds_read_b128 v[84:87], v116 offset:18432
	ds_read_b128 v[88:91], v116 offset:20736
	ds_read_b128 v[92:95], v116 offset:23040
	ds_read_b128 v[96:99], v116 offset:25344
	s_waitcnt lgkmcnt(3)
	v_mfma_f32_16x16x32_bf16 v[44:47], v[0:3], v[84:87], v[44:47]
	s_waitcnt lgkmcnt(2)
	v_mfma_f32_16x16x32_bf16 v[48:51], v[0:3], v[88:91], v[48:51]
	s_waitcnt lgkmcnt(1)
	v_mfma_f32_16x16x32_bf16 v[52:55], v[0:3], v[92:95], v[52:55]
	s_waitcnt lgkmcnt(0)
	v_mfma_f32_16x16x32_bf16 v[0:3], v[0:3], v[96:99], v[12:15]
	v_mfma_f32_16x16x32_bf16 v[12:15], v[4:7], v[84:87], v[40:43]
	v_mfma_f32_16x16x32_bf16 v[40:43], v[4:7], v[88:91], v[56:59]
	v_mfma_f32_16x16x32_bf16 v[100:103], v[4:7], v[92:95], v[60:63]
	v_mfma_f32_16x16x32_bf16 v[4:7], v[4:7], v[96:99], v[16:19]
	v_mfma_f32_16x16x32_bf16 v[16:19], v[8:11], v[84:87], v[68:71]
	v_mfma_f32_16x16x32_bf16 v[68:71], v[8:11], v[88:91], v[72:75]
	v_mfma_f32_16x16x32_bf16 v[72:75], v[8:11], v[92:95], v[76:79]
	v_mfma_f32_16x16x32_bf16 v[8:11], v[8:11], v[96:99], v[20:23]
	v_mfma_f32_16x16x32_bf16 v[76:79], v[80:83], v[84:87], v[28:31]
	v_mfma_f32_16x16x32_bf16 v[84:87], v[80:83], v[88:91], v[32:35]
	v_mfma_f32_16x16x32_bf16 v[88:91], v[80:83], v[92:95], v[36:39]
	v_mfma_f32_16x16x32_bf16 v[80:83], v[80:83], v[96:99], v[24:27]
	ds_read_b128 v[20:23], v114 offset:36928
	s_nop 1
	ds_read_b128 v[24:27], v114 offset:39232
	ds_read_b128 v[92:95], v114 offset:41536
	ds_read_b128 v[96:99], v114 offset:43840
	ds_read_b128 v[104:107], v116 offset:18496
	ds_read_b128 v[108:111], v116 offset:20800
	ds_read_b128 v[112:115], v116 offset:23104
	ds_read_b128 v[116:119], v116 offset:25408
	s_waitcnt lgkmcnt(0)
	s_barrier
	s_load_dwordx2 s[2:3], s[0:1], 0xc0
	s_load_dwordx4 s[12:15], s[0:1], 0xd0
	v_mfma_f32_16x16x32_bf16 v[60:63], v[20:23], v[104:107], v[44:47]
	v_mfma_f32_16x16x32_bf16 v[44:47], v[24:27], v[104:107], v[12:15]
	v_mfma_f32_16x16x32_bf16 v[40:43], v[24:27], v[108:111], v[40:43]
	v_mfma_f32_16x16x32_bf16 v[36:39], v[24:27], v[112:115], v[100:103]
	v_mfma_f32_16x16x32_bf16 v[32:35], v[24:27], v[116:119], v[4:7]
	v_mfma_f32_16x16x32_bf16 v[24:27], v[92:95], v[108:111], v[68:71]
	v_mfma_f32_16x16x32_bf16 v[56:59], v[20:23], v[108:111], v[48:51]
	v_mfma_f32_16x16x32_bf16 v[52:55], v[20:23], v[112:115], v[52:55]
	v_mfma_f32_16x16x32_bf16 v[48:51], v[20:23], v[116:119], v[0:3]
	v_mfma_f32_16x16x32_bf16 v[20:23], v[92:95], v[112:115], v[72:75]
	v_mfma_f32_16x16x32_bf16 v[0:3], v[96:99], v[116:119], v[80:83]
	v_mfma_f32_16x16x32_bf16 v[12:15], v[96:99], v[104:107], v[76:79]
	v_mfma_f32_16x16x32_bf16 v[28:31], v[92:95], v[104:107], v[16:19]
	v_mfma_f32_16x16x32_bf16 v[16:19], v[92:95], v[116:119], v[8:11]
	v_mfma_f32_16x16x32_bf16 v[8:11], v[96:99], v[108:111], v[84:87]
	v_mfma_f32_16x16x32_bf16 v[4:7], v[96:99], v[112:115], v[88:91]
	v_and_b32_e32 v65, 0xc0, v65
	v_lshlrev_b32_e32 v66, 2, v66
	v_or3_b32 v66, v66, v65, s4
	v_and_b32_e32 v179, 0xff, v66
	v_mul_u32_u24_e32 v179, 0x90, v179
	v_and_b32_e32 v188, 63, v64
	v_lshl_add_u32 v179, v188, 1, v179
	v_bfe_u32 v188, v64, 6, 1
	v_mul_u32_u24_e32 v188, 0x9000, v188
	v_add_u32_e32 v178, v179, v188
	v_lshl_add_u32 v245, v66, 10, v64
	v_lshlrev_b32_e32 v245, 2, v245
	v_add_u32_e32 v244, s6, v64
	v_lshlrev_b32_e32 v244, 2, v244
	s_waitcnt lgkmcnt(0)
	global_load_dword v67, v244, s[14:15]
	global_load_dword v72, v244, s[14:15] offset:64
	global_load_dword v250, v244, s[2:3]
	global_load_dword v251, v244, s[12:13]
	global_load_dword v246, v244, s[2:3] offset:64
	global_load_dword v247, v244, s[12:13] offset:64
	s_waitcnt vmcnt(0)
	v_mov_b32_e32 v243, v72
	s_mov_b32 s2, 0x3f2aaaab
	v_mul_f32_e32 v67, 0xbfb8aa3b, v67
	v_exp_f32_e32 v67, v67
	s_nop 0
	v_add_f32_e32 v70, 1.0, v67
	v_add_f32_e32 v68, -1.0, v70
	v_sub_f32_e32 v69, v68, v70
	v_add_f32_e32 v69, 1.0, v69
	v_sub_f32_e32 v68, v67, v68
	v_add_f32_e32 v71, v68, v69
	v_frexp_mant_f32_e32 v68, v70
	v_cmp_gt_f32_e32 vcc, s2, v68
	s_nop 1
	v_cvt_f64_f32_e32 v[68:69], v70
	v_frexp_exp_i32_f64_e32 v68, v[68:69]
	s_mov_b32 s2, 0x3f317218
	v_subbrev_co_u32_e32 v84, vcc, 0, v68, vcc
	s_nop 1
	v_sub_u32_e32 v68, 0, v84
	v_ldexp_f32 v69, v70, v68
	v_add_f32_e32 v70, -1.0, v69
	v_add_f32_e32 v78, 1.0, v69
	v_ldexp_f32 v68, v71, v68
	v_add_f32_e32 v71, 1.0, v70
	v_add_f32_e32 v79, -1.0, v78
	v_sub_f32_e32 v71, v69, v71
	v_sub_f32_e32 v69, v69, v79
	v_add_f32_e32 v71, v68, v71
	v_add_f32_e32 v68, v68, v69
	v_add_f32_e32 v85, v78, v68
	v_rcp_f32_e32 v87, v85
	s_nop 0
	v_sub_f32_e32 v69, v85, v78
	v_sub_f32_e32 v86, v68, v69
	v_add_f32_e32 v69, v70, v71
	v_sub_f32_e32 v68, v69, v70
	v_mul_f32_e32 v89, v69, v87
	v_mul_f32_e32 v70, v85, v89
	v_fma_f32 v78, v89, v85, -v70
	v_fmac_f32_e32 v78, v89, v86
	v_sub_f32_e32 v88, v71, v68
	v_add_f32_e32 v68, v70, v78
	v_sub_f32_e32 v71, v69, v68
	v_pk_add_f32 v[80:81], v[68:69], v[70:71] neg_lo:[0,1] neg_hi:[0,1]
	v_mov_b32_e32 v79, v68
	v_pk_add_f32 v[68:69], v[80:81], v[78:79] neg_lo:[0,1] neg_hi:[0,1]
	v_add_f32_e32 v69, v88, v69
	v_add_f32_e32 v68, v68, v69
	v_add_f32_e32 v69, v71, v68
	v_mul_f32_e32 v88, v87, v69
	v_mul_f32_e32 v70, v85, v88
	v_fma_f32 v78, v88, v85, -v70
	v_fmac_f32_e32 v78, v88, v86
	v_sub_f32_e32 v71, v71, v69
	v_add_f32_e32 v85, v68, v71
	v_add_f32_e32 v68, v70, v78
	v_sub_f32_e32 v71, v69, v68
	v_pk_add_f32 v[80:81], v[68:69], v[70:71] neg_lo:[0,1] neg_hi:[0,1]
	v_mov_b32_e32 v79, v68
	v_pk_add_f32 v[68:69], v[80:81], v[78:79] neg_lo:[0,1] neg_hi:[0,1]
	v_add_f32_e32 v69, v85, v69
	v_add_f32_e32 v68, v68, v69
; template <int EPI>
; __device__ __forceinline__ void gemm_tile(const Params& p, const EpiArgs& ea, const bf16_t* __restrict__ A, int lda,
;                                           const bf16_t* __restrict__ Bt, int K, int m0, int n0, char* smem) {
;     ...
;         int ch = (n0 >> 1) + wn * 32 + nh * 16 + fr;
;         float ba = p.lru_b_a[ea.dir * 1024 + ch], bx = p.lru_b_x[ea.dir * 1024 + ch];
;         float sp8 = -8.0f * log1pf(__expf(-p.lru_lam[ea.dir * 1024 + ch]));
	v_add_f32_e32 v69, v89, v88
	v_add_f32_e32 v68, v71, v68
	v_sub_f32_e32 v70, v69, v89
	v_mul_f32_e32 v68, v87, v68
	v_sub_f32_e32 v70, v88, v70
	v_add_f32_e32 v70, v70, v68
	v_add_f32_e32 v78, v69, v70
	v_mul_f32_e32 v79, v78, v78
	v_fmamk_f32 v68, v79, 0x3e9b6dac, v165
	v_fmaak_f32 v171, v79, v68, 0x3f2aaada
	v_cvt_f32_i32_e32 v68, v84
	v_sub_f32_e32 v69, v78, v69
	v_sub_f32_e32 v69, v70, v69
	v_ldexp_f32 v80, v69, 1
	v_mul_f32_e32 v69, v78, v79
	v_ldexp_f32 v71, v78, 1
	v_pk_mul_f32 v[78:79], v[68:69], v[170:171]
	v_fma_f32 v70, v68, s2, -v78
	v_fmac_f32_e32 v70, 0xb102e308, v68
	v_pk_add_f32 v[68:69], v[78:79], v[70:71]
	s_mov_b32 s2, 0x7f800000
	v_sub_f32_e32 v71, v69, v71
	v_sub_f32_e32 v71, v79, v71
	v_add_f32_e32 v81, v80, v71
	v_mov_b32_e32 v80, v78
	v_pk_add_f32 v[78:79], v[68:69], v[78:79] neg_lo:[0,1] neg_hi:[0,1]
	v_pk_add_f32 v[84:85], v[68:69], v[80:81]
	v_mov_b32_e32 v71, v68
	v_mov_b32_e32 v79, v85
	v_pk_add_f32 v[86:87], v[70:71], v[78:79] neg_lo:[0,1] neg_hi:[0,1]
	v_pk_add_f32 v[70:71], v[70:71], v[78:79]
	v_mov_b32_e32 v80, v81
	v_pk_add_f32 v[78:79], v[70:71], v[68:69] op_sel:[1,0] op_sel_hi:[0,1] neg_lo:[0,1] neg_hi:[0,1]
	v_pk_add_f32 v[88:89], v[84:85], v[78:79] op_sel_hi:[1,0] neg_lo:[0,1] neg_hi:[0,1]
	v_mov_b32_e32 v84, v85
	v_mov_b32_e32 v85, v71
	v_pk_mov_b32 v[78:79], v[68:69], v[78:79] op_sel:[1,0]
	v_mov_b32_e32 v81, v68
	v_pk_add_f32 v[78:79], v[84:85], v[78:79] neg_lo:[0,1] neg_hi:[0,1]
	v_mov_b32_e32 v88, v86
	v_pk_add_f32 v[68:69], v[80:81], v[78:79] neg_lo:[0,1] neg_hi:[0,1]
	v_mov_b32_e32 v87, v71
	v_pk_add_f32 v[78:79], v[88:89], v[68:69]
	v_cmp_neq_f32_e32 vcc, s2, v67
	s_nop 1
	v_pk_add_f32 v[80:81], v[78:79], v[78:79] op_sel:[0,1] op_sel_hi:[1,0]
	s_mov_b32 s2, 0x33800000
	v_pk_add_f32 v[70:71], v[70:71], v[80:81] op_sel:[1,0] op_sel_hi:[0,1]
	v_mov_b32_e32 v79, v70
	v_pk_add_f32 v[84:85], v[78:79], v[86:87] neg_lo:[0,1] neg_hi:[0,1]
	v_mov_b32_e32 v69, v80
	v_sub_f32_e32 v71, v78, v84
	v_pk_add_f32 v[68:69], v[68:69], v[84:85] neg_lo:[0,1] neg_hi:[0,1]
	v_sub_f32_e32 v71, v86, v71
	v_add_f32_e32 v68, v68, v71
	v_add_f32_e32 v68, v68, v69
	v_add_f32_e32 v68, v70, v68
	v_cndmask_b32_e32 v68, v225, v68, vcc
	v_cmp_ngt_f32_e32 vcc, -1.0, v67
	s_nop 1
	v_cndmask_b32_e32 v68, v226, v68, vcc
	v_cmp_neq_f32_e32 vcc, -1.0, v67
	s_nop 1
	v_cndmask_b32_e32 v68, v227, v68, vcc
	v_cmp_lt_f32_e64 vcc, |v67|, s2
	s_nop 1
	v_cndmask_b32_e32 v67, v68, v67, vcc
	v_mul_f32_e32 v84, 0xc1000000, v67
	v_mov_b32_e32 v248, v84
	v_mov_b32_e32 v72, v243
	s_mov_b32 s2, 0x3f2aaaab
	v_mul_f32_e32 v72, 0xbfb8aa3b, v72
	v_exp_f32_e32 v75, v72
	s_nop 0
	v_add_f32_e32 v76, 1.0, v75
	v_add_f32_e32 v72, -1.0, v76
	v_sub_f32_e32 v73, v72, v76
	v_add_f32_e32 v73, 1.0, v73
	v_sub_f32_e32 v72, v75, v72
	v_add_f32_e32 v77, v72, v73
	v_frexp_mant_f32_e32 v72, v76
	v_cmp_gt_f32_e32 vcc, s2, v72
	s_nop 1
	v_cvt_f64_f32_e32 v[72:73], v76
	v_frexp_exp_i32_f64_e32 v72, v[72:73]
	v_subbrev_co_u32_e32 v85, vcc, 0, v72, vcc
	s_nop 1
	v_sub_u32_e32 v72, 0, v85
	v_ldexp_f32 v73, v76, v72
	v_add_f32_e32 v76, -1.0, v73
	v_add_f32_e32 v86, 1.0, v73
	v_ldexp_f32 v72, v77, v72
	v_add_f32_e32 v77, 1.0, v76
	v_add_f32_e32 v87, -1.0, v86
	v_sub_f32_e32 v77, v73, v77
	v_sub_f32_e32 v73, v73, v87
	v_add_f32_e32 v77, v72, v77
	v_add_f32_e32 v72, v72, v73
	v_add_f32_e32 v90, v86, v72
	v_rcp_f32_e32 v92, v90
	s_nop 0
	v_sub_f32_e32 v73, v90, v86
	v_sub_f32_e32 v91, v72, v73
	v_add_f32_e32 v73, v76, v77
	v_mul_f32_e32 v94, v73, v92
	v_sub_f32_e32 v72, v73, v76
	v_mul_f32_e32 v76, v90, v94
	v_fma_f32 v86, v94, v90, -v76
	v_fmac_f32_e32 v86, v94, v91
	v_sub_f32_e32 v93, v77, v72
	v_add_f32_e32 v72, v76, v86
	v_sub_f32_e32 v77, v73, v72
	v_pk_add_f32 v[88:89], v[72:73], v[76:77] neg_lo:[0,1] neg_hi:[0,1]
	v_mov_b32_e32 v87, v72
	v_pk_add_f32 v[72:73], v[88:89], v[86:87] neg_lo:[0,1] neg_hi:[0,1]
	s_mov_b32 s2, 0x3f317218
	v_add_f32_e32 v73, v93, v73
	v_add_f32_e32 v72, v72, v73
	v_add_f32_e32 v73, v77, v72
	v_mul_f32_e32 v93, v92, v73
	v_mul_f32_e32 v76, v90, v93
	v_fma_f32 v86, v93, v90, -v76
	v_fmac_f32_e32 v86, v93, v91
	v_sub_f32_e32 v77, v77, v73
	v_add_f32_e32 v90, v72, v77
	v_add_f32_e32 v72, v76, v86
	v_sub_f32_e32 v77, v73, v72
	v_pk_add_f32 v[88:89], v[72:73], v[76:77] neg_lo:[0,1] neg_hi:[0,1]
	v_mov_b32_e32 v87, v72
	v_pk_add_f32 v[72:73], v[88:89], v[86:87] neg_lo:[0,1] neg_hi:[0,1]
	v_add_f32_e32 v73, v90, v73
	v_add_f32_e32 v72, v72, v73
	v_add_f32_e32 v73, v94, v93
	v_add_f32_e32 v72, v77, v72
	v_sub_f32_e32 v76, v73, v94
	v_mul_f32_e32 v72, v92, v72
	v_sub_f32_e32 v76, v93, v76
	v_add_f32_e32 v76, v76, v72
	v_add_f32_e32 v86, v73, v76
	v_mul_f32_e32 v87, v86, v86
	v_fmamk_f32 v72, v87, 0x3e9b6dac, v165
	v_fmaak_f32 v171, v87, v72, 0x3f2aaada
	v_cvt_f32_i32_e32 v72, v85
	v_sub_f32_e32 v73, v86, v73
	v_sub_f32_e32 v73, v76, v73
	v_ldexp_f32 v85, v73, 1
	v_mul_f32_e32 v73, v86, v87
	v_ldexp_f32 v77, v86, 1
	v_pk_mul_f32 v[86:87], v[72:73], v[170:171]
	v_fma_f32 v76, v72, s2, -v86
	v_fmac_f32_e32 v76, 0xb102e308, v72
	v_pk_add_f32 v[72:73], v[86:87], v[76:77]
	v_mov_b32_e32 v88, v86
	v_sub_f32_e32 v77, v73, v77
	v_sub_f32_e32 v77, v87, v77
	v_add_f32_e32 v89, v85, v77
	v_pk_add_f32 v[86:87], v[72:73], v[86:87] neg_lo:[0,1] neg_hi:[0,1]
	v_pk_add_f32 v[90:91], v[72:73], v[88:89]
	v_mov_b32_e32 v77, v72
	v_mov_b32_e32 v87, v91
	v_pk_add_f32 v[92:93], v[76:77], v[86:87] neg_lo:[0,1] neg_hi:[0,1]
	v_pk_add_f32 v[76:77], v[76:77], v[86:87]
	v_mov_b32_e32 v88, v89
	v_pk_add_f32 v[86:87], v[76:77], v[72:73] op_sel:[1,0] op_sel_hi:[0,1] neg_lo:[0,1] neg_hi:[0,1]
	v_pk_add_f32 v[94:95], v[90:91], v[86:87] op_sel_hi:[1,0] neg_lo:[0,1] neg_hi:[0,1]
; __device__ __forceinline__ float sigmoidf_(float x) { return __builtin_amdgcn_rcpf(1.0f + __expf(-x)); }
; template <int EPI>
; __device__ __forceinline__ void gemm_tile(const Params& p, const EpiArgs& ea, const bf16_t* __restrict__ A, int lda,
;                                           const bf16_t* __restrict__ Bt, int K, int m0, int n0, char* smem) {
;     ...
;         float ba = p.lru_b_a[ea.dir * 1024 + ch], bx = p.lru_b_x[ea.dir * 1024 + ch];
;         float sp8 = -8.0f * log1pf(__expf(-p.lru_lam[ea.dir * 1024 + ch]));
; #pragma unroll
;         for (int j = 0; j < 4; ++j) {
;           float r = sigmoidf_(acc[mi][nh * 2][j] + ba);
;           float ig = sigmoidf_(acc[mi][nh * 2 + 1][j] + bx);
;           float la = r * sp8;
;           float x2 = 2.0f * la;
;           float poly = -x2 * (1.0f + x2 * (0.5f + x2 * (0.16666667f + x2 * (0.041666668f + x2 * (0.008333334f + x2 * 0.0013888889f)))));
;           float em = (x2 < -0.3f) ? (1.0f - __expf(x2)) : poly;
	v_mov_b32_e32 v90, v91
	v_mov_b32_e32 v91, v77
	v_pk_mov_b32 v[86:87], v[72:73], v[86:87] op_sel:[1,0]
	v_mov_b32_e32 v89, v72
	v_pk_add_f32 v[86:87], v[90:91], v[86:87] neg_lo:[0,1] neg_hi:[0,1]
	v_mov_b32_e32 v94, v92
	v_pk_add_f32 v[72:73], v[88:89], v[86:87] neg_lo:[0,1] neg_hi:[0,1]
	v_mov_b32_e32 v93, v77
	v_pk_add_f32 v[86:87], v[94:95], v[72:73]
	s_mov_b32 s2, 0x7f800000
	v_pk_add_f32 v[88:89], v[86:87], v[86:87] op_sel:[0,1] op_sel_hi:[1,0]
	v_cmp_neq_f32_e32 vcc, s2, v75
	s_nop 1
	v_pk_add_f32 v[76:77], v[76:77], v[88:89] op_sel:[1,0] op_sel_hi:[0,1]
	v_mov_b32_e32 v87, v76
	v_pk_add_f32 v[90:91], v[86:87], v[92:93] neg_lo:[0,1] neg_hi:[0,1]
	v_mov_b32_e32 v73, v88
	v_sub_f32_e32 v77, v86, v90
	v_pk_add_f32 v[72:73], v[72:73], v[90:91] neg_lo:[0,1] neg_hi:[0,1]
	v_sub_f32_e32 v77, v92, v77
	v_add_f32_e32 v72, v72, v77
	v_add_f32_e32 v72, v72, v73
	v_add_f32_e32 v72, v76, v72
	v_cndmask_b32_e32 v72, v225, v72, vcc
	v_cmp_ngt_f32_e32 vcc, -1.0, v75
	s_nop 1
	s_mov_b32 s2, 0x33800000
	v_cndmask_b32_e32 v72, v226, v72, vcc
	v_cmp_neq_f32_e32 vcc, -1.0, v75
	s_nop 1
	v_cndmask_b32_e32 v72, v227, v72, vcc
	v_cmp_lt_f32_e64 vcc, |v75|, s2
	s_nop 1
	v_cndmask_b32_e32 v72, v72, v75, vcc
	v_mul_f32_e32 v72, 0xc1000000, v72
	v_mov_b32_e32 v249, v72
	ds_read_u16 v197, v178 offset:0
	ds_read_u16 v198, v178 offset:144
	ds_read_u16 v199, v178 offset:288
	ds_read_u16 v200, v178 offset:432
	ds_read_u16 v201, v178 offset:32
	ds_read_u16 v202, v178 offset:176
	ds_read_u16 v203, v178 offset:320
	ds_read_u16 v204, v178 offset:464
	v_add_u32_e32 v236, 0x0, v245
	v_add_u32_e32 v237, 0x1000, v245
	v_add_u32_e32 v238, 0x2000, v245
	v_add_u32_e32 v239, 0x3000, v245
	v_add_f32_e32 v92, v60, v250
	v_add_f32_e32 v93, v61, v250
	v_add_f32_e32 v94, v62, v250
	v_add_f32_e32 v95, v63, v250
	v_add_f32_e32 v96, v52, v246
	v_add_f32_e32 v97, v53, v246
	v_add_f32_e32 v98, v54, v246
	v_add_f32_e32 v99, v55, v246
	v_add_f32_e32 v100, v56, v251
	v_add_f32_e32 v101, v57, v251
	v_add_f32_e32 v102, v58, v251
	v_add_f32_e32 v103, v59, v251
	v_add_f32_e32 v104, v48, v247
	v_add_f32_e32 v105, v49, v247
	v_add_f32_e32 v106, v50, v247
	v_add_f32_e32 v107, v51, v247
	v_mul_f32_e32 v92, 0xbfb8aa3b, v92
	v_mul_f32_e32 v93, 0xbfb8aa3b, v93
	v_mul_f32_e32 v94, 0xbfb8aa3b, v94
	v_mul_f32_e32 v95, 0xbfb8aa3b, v95
	v_mul_f32_e32 v96, 0xbfb8aa3b, v96
	v_mul_f32_e32 v97, 0xbfb8aa3b, v97
	v_mul_f32_e32 v98, 0xbfb8aa3b, v98
	v_mul_f32_e32 v99, 0xbfb8aa3b, v99
	v_mul_f32_e32 v100, 0xbfb8aa3b, v100
	v_mul_f32_e32 v101, 0xbfb8aa3b, v101
	v_mul_f32_e32 v102, 0xbfb8aa3b, v102
	v_mul_f32_e32 v103, 0xbfb8aa3b, v103
	v_mul_f32_e32 v104, 0xbfb8aa3b, v104
	v_mul_f32_e32 v105, 0xbfb8aa3b, v105
	v_mul_f32_e32 v106, 0xbfb8aa3b, v106
	v_mul_f32_e32 v107, 0xbfb8aa3b, v107
	v_exp_f32_e32 v92, v92
	v_exp_f32_e32 v93, v93
	v_exp_f32_e32 v94, v94
	v_exp_f32_e32 v95, v95
	v_exp_f32_e32 v96, v96
	v_exp_f32_e32 v97, v97
	v_exp_f32_e32 v98, v98
	v_exp_f32_e32 v99, v99
	v_exp_f32_e32 v100, v100
	v_exp_f32_e32 v101, v101
	v_exp_f32_e32 v102, v102
	v_exp_f32_e32 v103, v103
	v_exp_f32_e32 v104, v104
	v_exp_f32_e32 v105, v105
	v_exp_f32_e32 v106, v106
	v_exp_f32_e32 v107, v107
	v_add_f32_e32 v92, 1.0, v92
	v_add_f32_e32 v93, 1.0, v93
	v_add_f32_e32 v94, 1.0, v94
	v_add_f32_e32 v95, 1.0, v95
	v_add_f32_e32 v96, 1.0, v96
	v_add_f32_e32 v97, 1.0, v97
	v_add_f32_e32 v98, 1.0, v98
	v_add_f32_e32 v99, 1.0, v99
	v_add_f32_e32 v100, 1.0, v100
	v_add_f32_e32 v101, 1.0, v101
	v_add_f32_e32 v102, 1.0, v102
	v_add_f32_e32 v103, 1.0, v103
	v_add_f32_e32 v104, 1.0, v104
	v_add_f32_e32 v105, 1.0, v105
	v_add_f32_e32 v106, 1.0, v106
	v_add_f32_e32 v107, 1.0, v107
	v_rcp_f32_e32 v92, v92
	v_rcp_f32_e32 v93, v93
	v_rcp_f32_e32 v94, v94
	v_rcp_f32_e32 v95, v95
	v_rcp_f32_e32 v96, v96
	v_rcp_f32_e32 v97, v97
	v_rcp_f32_e32 v98, v98
	v_rcp_f32_e32 v99, v99
	v_rcp_f32_e32 v100, v100
	v_rcp_f32_e32 v101, v101
	v_rcp_f32_e32 v102, v102
	v_rcp_f32_e32 v103, v103
	v_rcp_f32_e32 v104, v104
	v_rcp_f32_e32 v105, v105
	v_rcp_f32_e32 v106, v106
	v_rcp_f32_e32 v107, v107
	v_mul_f32_e32 v92, v92, v248
	v_mul_f32_e32 v93, v93, v248
	v_mul_f32_e32 v94, v94, v248
	v_mul_f32_e32 v95, v95, v248
	v_mul_f32_e32 v96, v96, v249
	v_mul_f32_e32 v97, v97, v249
	v_mul_f32_e32 v98, v98, v249
	v_mul_f32_e32 v99, v99, v249
	v_add_f32_e32 v108, v92, v92
	v_add_f32_e32 v109, v93, v93
	v_add_f32_e32 v110, v94, v94
	v_add_f32_e32 v111, v95, v95
	v_add_f32_e32 v112, v96, v96
	v_add_f32_e32 v113, v97, v97
	v_add_f32_e32 v114, v98, v98
	v_add_f32_e32 v115, v99, v99
	v_cmp_ngt_f32_e64 s[60:61], s9, v108
	v_cmp_ngt_f32_e64 s[62:63], s9, v109
	v_cmp_ngt_f32_e64 s[64:65], s9, v110
	v_cmp_ngt_f32_e64 s[66:67], s9, v111
	v_cmp_ngt_f32_e64 s[68:69], s9, v112
	v_cmp_ngt_f32_e64 s[70:71], s9, v113
	v_cmp_ngt_f32_e64 s[72:73], s9, v114
	v_cmp_ngt_f32_e64 s[74:75], s9, v115
	v_fmamk_f32 v205, v108, 0x3ab60b61, v169
	v_fmamk_f32 v206, v109, 0x3ab60b61, v169
	v_fmamk_f32 v207, v110, 0x3ab60b61, v169
	v_fmamk_f32 v208, v111, 0x3ab60b61, v169
	v_fmamk_f32 v209, v112, 0x3ab60b61, v169
	v_fmamk_f32 v210, v113, 0x3ab60b61, v169
	v_fmamk_f32 v211, v114, 0x3ab60b61, v169
	v_fmamk_f32 v212, v115, 0x3ab60b61, v169
	v_fmaak_f32 v205, v108, v205, 0x3d2aaaab
	v_fmaak_f32 v206, v109, v206, 0x3d2aaaab
	v_fmaak_f32 v207, v110, v207, 0x3d2aaaab
	v_fmaak_f32 v208, v111, v208, 0x3d2aaaab
	v_fmaak_f32 v209, v112, v209, 0x3d2aaaab
	v_fmaak_f32 v210, v113, v210, 0x3d2aaaab
	v_fmaak_f32 v211, v114, v211, 0x3d2aaaab
	v_fmaak_f32 v212, v115, v212, 0x3d2aaaab
	v_fmaak_f32 v205, v108, v205, 0x3e2aaaab
	v_fmaak_f32 v206, v109, v206, 0x3e2aaaab
	v_fmaak_f32 v207, v110, v207, 0x3e2aaaab
;   __host__ __device__ __forceinline__ bf16_t* XC() const { return (bf16_t*)(wsl() + OFF_FFN); }
; __device__ __forceinline__ float bf2f(bf16_t h) { return __uint_as_float(((uint32_t)h) << 16); }
; __device__ __forceinline__ uint32_t pack2(float a, float b) { uint32_t r; asm("v_cvt_pk_bf16_f32 %0, %1, %2" : "=v"(r) : "v"(a), "v"(b)); return r; }
; __device__ __forceinline__ float sigmoidf_(float x) { return __builtin_amdgcn_rcpf(1.0f + __expf(-x)); }
; template <int EPI>
; __device__ __forceinline__ void gemm_tile(const Params& p, const EpiArgs& ea, const bf16_t* __restrict__ A, int lda,
;                                           const bf16_t* __restrict__ Bt, int K, int m0, int n0, char* smem) {
;     ...
;           float r = sigmoidf_(acc[mi][nh * 2][j] + ba);
;           float ig = sigmoidf_(acc[mi][nh * 2 + 1][j] + bx);
;           float la = r * sp8;
;           float x2 = 2.0f * la;
;           float poly = -x2 * (1.0f + x2 * (0.5f + x2 * (0.16666667f + x2 * (0.041666668f + x2 * (0.008333334f + x2 * 0.0013888889f)))));
;           float em = (x2 < -0.3f) ? (1.0f - __expf(x2)) : poly;
;           float u = bf2f(p.XC()[(size_t)(r0 + j) * D + ch]);
;           float inp = __builtin_amdgcn_sqrtf(fmaxf(em, 0.0f)) * (ig * u);
;           ea.outu[(size_t)(r0 + j) * D + ch] = pack2(la, inp);
	v_fmaak_f32 v208, v111, v208, 0x3e2aaaab
	v_fmaak_f32 v209, v112, v209, 0x3e2aaaab
	v_fmaak_f32 v210, v113, v210, 0x3e2aaaab
	v_fmaak_f32 v211, v114, v211, 0x3e2aaaab
	v_fmaak_f32 v212, v115, v212, 0x3e2aaaab
	v_fma_f32 v205, v108, v205, 0.5
	v_fma_f32 v206, v109, v206, 0.5
	v_fma_f32 v207, v110, v207, 0.5
	v_fma_f32 v208, v111, v208, 0.5
	v_fma_f32 v209, v112, v209, 0.5
	v_fma_f32 v210, v113, v210, 0.5
	v_fma_f32 v211, v114, v211, 0.5
	v_fma_f32 v212, v115, v212, 0.5
	v_fma_f32 v205, v108, v205, 1.0
	v_fma_f32 v206, v109, v206, 1.0
	v_fma_f32 v207, v110, v207, 1.0
	v_fma_f32 v208, v111, v208, 1.0
	v_fma_f32 v209, v112, v209, 1.0
	v_fma_f32 v210, v113, v210, 1.0
	v_fma_f32 v211, v114, v211, 1.0
	v_fma_f32 v212, v115, v212, 1.0
	v_mul_f32_e64 v205, v205, -v108
	v_mul_f32_e64 v206, v206, -v109
	v_mul_f32_e64 v207, v207, -v110
	v_mul_f32_e64 v208, v208, -v111
	v_mul_f32_e64 v209, v209, -v112
	v_mul_f32_e64 v210, v210, -v113
	v_mul_f32_e64 v211, v211, -v114
	v_mul_f32_e64 v212, v212, -v115
	v_mul_f32_e32 v189, 0x3fb8aa3b, v108
	v_mul_f32_e32 v190, 0x3fb8aa3b, v109
	v_mul_f32_e32 v191, 0x3fb8aa3b, v110
	v_mul_f32_e32 v192, 0x3fb8aa3b, v111
	v_mul_f32_e32 v193, 0x3fb8aa3b, v112
	v_mul_f32_e32 v194, 0x3fb8aa3b, v113
	v_mul_f32_e32 v195, 0x3fb8aa3b, v114
	v_mul_f32_e32 v196, 0x3fb8aa3b, v115
	v_exp_f32_e32 v189, v189
	v_exp_f32_e32 v190, v190
	v_exp_f32_e32 v191, v191
	v_exp_f32_e32 v192, v192
	v_exp_f32_e32 v193, v193
	v_exp_f32_e32 v194, v194
	v_exp_f32_e32 v195, v195
	v_exp_f32_e32 v196, v196
	v_sub_f32_e32 v189, 1.0, v189
	v_sub_f32_e32 v190, 1.0, v190
	v_sub_f32_e32 v191, 1.0, v191
	v_sub_f32_e32 v192, 1.0, v192
	v_sub_f32_e32 v193, 1.0, v193
	v_sub_f32_e32 v194, 1.0, v194
	v_sub_f32_e32 v195, 1.0, v195
	v_sub_f32_e32 v196, 1.0, v196
	v_cndmask_b32_e64 v189, v189, v205, s[60:61]
	v_cndmask_b32_e64 v190, v190, v206, s[62:63]
	v_cndmask_b32_e64 v191, v191, v207, s[64:65]
	v_cndmask_b32_e64 v192, v192, v208, s[66:67]
	v_cndmask_b32_e64 v193, v193, v209, s[68:69]
	v_cndmask_b32_e64 v194, v194, v210, s[70:71]
	v_cndmask_b32_e64 v195, v195, v211, s[72:73]
	v_cndmask_b32_e64 v196, v196, v212, s[74:75]
	v_max_f32_e32 v189, v189, v189
	v_max_f32_e32 v190, v190, v190
	v_max_f32_e32 v191, v191, v191
	v_max_f32_e32 v192, v192, v192
	v_max_f32_e32 v193, v193, v193
	v_max_f32_e32 v194, v194, v194
	v_max_f32_e32 v195, v195, v195
	v_max_f32_e32 v196, v196, v196
	v_max_f32_e32 v189, 0, v189
	v_max_f32_e32 v190, 0, v190
	v_max_f32_e32 v191, 0, v191
	v_max_f32_e32 v192, 0, v192
	v_max_f32_e32 v193, 0, v193
	v_max_f32_e32 v194, 0, v194
	v_max_f32_e32 v195, 0, v195
	v_max_f32_e32 v196, 0, v196
	v_sqrt_f32_e32 v189, v189
	v_sqrt_f32_e32 v190, v190
	v_sqrt_f32_e32 v191, v191
	v_sqrt_f32_e32 v192, v192
	v_sqrt_f32_e32 v193, v193
	v_sqrt_f32_e32 v194, v194
	v_sqrt_f32_e32 v195, v195
	v_sqrt_f32_e32 v196, v196
	s_waitcnt lgkmcnt(0)
	v_lshlrev_b32_e32 v197, 16, v197
	v_lshlrev_b32_e32 v198, 16, v198
	v_lshlrev_b32_e32 v199, 16, v199
	v_lshlrev_b32_e32 v200, 16, v200
	v_lshlrev_b32_e32 v201, 16, v201
	v_lshlrev_b32_e32 v202, 16, v202
	v_lshlrev_b32_e32 v203, 16, v203
	v_lshlrev_b32_e32 v204, 16, v204
	v_mul_f32_e32 v100, v100, v197
	v_mul_f32_e32 v101, v101, v198
	v_mul_f32_e32 v102, v102, v199
	v_mul_f32_e32 v103, v103, v200
	v_mul_f32_e32 v104, v104, v201
	v_mul_f32_e32 v105, v105, v202
	v_mul_f32_e32 v106, v106, v203
	v_mul_f32_e32 v107, v107, v204
	v_mul_f32_e32 v100, v189, v100
	v_mul_f32_e32 v101, v190, v101
	v_mul_f32_e32 v102, v191, v102
	v_mul_f32_e32 v103, v192, v103
	v_mul_f32_e32 v104, v193, v104
	v_mul_f32_e32 v105, v194, v105
	v_mul_f32_e32 v106, v195, v106
	v_mul_f32_e32 v107, v196, v107
	v_cvt_pk_bf16_f32 v100, v92, v100
	v_cvt_pk_bf16_f32 v101, v93, v101
	v_cvt_pk_bf16_f32 v102, v94, v102
	v_cvt_pk_bf16_f32 v103, v95, v103
	v_cvt_pk_bf16_f32 v104, v96, v104
	v_cvt_pk_bf16_f32 v105, v97, v105
	v_cvt_pk_bf16_f32 v106, v98, v106
	v_cvt_pk_bf16_f32 v107, v99, v107
	global_store_dword v236, v100, s[42:43]
	global_store_dword v237, v101, s[42:43]
	global_store_dword v238, v102, s[42:43]
	global_store_dword v239, v103, s[42:43]
	global_store_dword v236, v104, s[42:43] offset:64
	global_store_dword v237, v105, s[42:43] offset:64
	global_store_dword v238, v106, s[42:43] offset:64
	global_store_dword v239, v107, s[42:43] offset:64
	ds_read_u16 v197, v178 offset:2304
	ds_read_u16 v198, v178 offset:2448
	ds_read_u16 v199, v178 offset:2592
	ds_read_u16 v200, v178 offset:2736
	ds_read_u16 v201, v178 offset:2336
	ds_read_u16 v202, v178 offset:2480
	ds_read_u16 v203, v178 offset:2624
	ds_read_u16 v204, v178 offset:2768
	v_add_u32_e32 v236, 0x10000, v245
	v_add_u32_e32 v237, 0x11000, v245
	v_add_u32_e32 v238, 0x12000, v245
	v_add_u32_e32 v239, 0x13000, v245
	v_add_f32_e32 v92, v44, v250
	v_add_f32_e32 v93, v45, v250
	v_add_f32_e32 v94, v46, v250
	v_add_f32_e32 v95, v47, v250
	v_add_f32_e32 v96, v36, v246
	v_add_f32_e32 v97, v37, v246
	v_add_f32_e32 v98, v38, v246
	v_add_f32_e32 v99, v39, v246
	v_add_f32_e32 v100, v40, v251
	v_add_f32_e32 v101, v41, v251
	v_add_f32_e32 v102, v42, v251
	v_add_f32_e32 v103, v43, v251
	v_add_f32_e32 v104, v32, v247
	v_add_f32_e32 v105, v33, v247
	v_add_f32_e32 v106, v34, v247
	v_add_f32_e32 v107, v35, v247
	v_mul_f32_e32 v92, 0xbfb8aa3b, v92
	v_mul_f32_e32 v93, 0xbfb8aa3b, v93
	v_mul_f32_e32 v94, 0xbfb8aa3b, v94
	v_mul_f32_e32 v95, 0xbfb8aa3b, v95
	v_mul_f32_e32 v96, 0xbfb8aa3b, v96
	v_mul_f32_e32 v97, 0xbfb8aa3b, v97
	v_mul_f32_e32 v98, 0xbfb8aa3b, v98
	v_mul_f32_e32 v99, 0xbfb8aa3b, v99
	v_mul_f32_e32 v100, 0xbfb8aa3b, v100
	v_mul_f32_e32 v101, 0xbfb8aa3b, v101
	v_mul_f32_e32 v102, 0xbfb8aa3b, v102
	v_mul_f32_e32 v103, 0xbfb8aa3b, v103
; __device__ __forceinline__ float sigmoidf_(float x) { return __builtin_amdgcn_rcpf(1.0f + __expf(-x)); }
; template <int EPI>
; __device__ __forceinline__ void gemm_tile(const Params& p, const EpiArgs& ea, const bf16_t* __restrict__ A, int lda,
;                                           const bf16_t* __restrict__ Bt, int K, int m0, int n0, char* smem) {
;     ...
;           float r = sigmoidf_(acc[mi][nh * 2][j] + ba);
;           float ig = sigmoidf_(acc[mi][nh * 2 + 1][j] + bx);
;           float la = r * sp8;
;           float x2 = 2.0f * la;
;           float poly = -x2 * (1.0f + x2 * (0.5f + x2 * (0.16666667f + x2 * (0.041666668f + x2 * (0.008333334f + x2 * 0.0013888889f)))));
;           float em = (x2 < -0.3f) ? (1.0f - __expf(x2)) : poly;
	v_mul_f32_e32 v104, 0xbfb8aa3b, v104
	v_mul_f32_e32 v105, 0xbfb8aa3b, v105
	v_mul_f32_e32 v106, 0xbfb8aa3b, v106
	v_mul_f32_e32 v107, 0xbfb8aa3b, v107
	v_exp_f32_e32 v92, v92
	v_exp_f32_e32 v93, v93
	v_exp_f32_e32 v94, v94
	v_exp_f32_e32 v95, v95
	v_exp_f32_e32 v96, v96
	v_exp_f32_e32 v97, v97
	v_exp_f32_e32 v98, v98
	v_exp_f32_e32 v99, v99
	v_exp_f32_e32 v100, v100
	v_exp_f32_e32 v101, v101
	v_exp_f32_e32 v102, v102
	v_exp_f32_e32 v103, v103
	v_exp_f32_e32 v104, v104
	v_exp_f32_e32 v105, v105
	v_exp_f32_e32 v106, v106
	v_exp_f32_e32 v107, v107
	v_add_f32_e32 v92, 1.0, v92
	v_add_f32_e32 v93, 1.0, v93
	v_add_f32_e32 v94, 1.0, v94
	v_add_f32_e32 v95, 1.0, v95
	v_add_f32_e32 v96, 1.0, v96
	v_add_f32_e32 v97, 1.0, v97
	v_add_f32_e32 v98, 1.0, v98
	v_add_f32_e32 v99, 1.0, v99
	v_add_f32_e32 v100, 1.0, v100
	v_add_f32_e32 v101, 1.0, v101
	v_add_f32_e32 v102, 1.0, v102
	v_add_f32_e32 v103, 1.0, v103
	v_add_f32_e32 v104, 1.0, v104
	v_add_f32_e32 v105, 1.0, v105
	v_add_f32_e32 v106, 1.0, v106
	v_add_f32_e32 v107, 1.0, v107
	v_rcp_f32_e32 v92, v92
	v_rcp_f32_e32 v93, v93
	v_rcp_f32_e32 v94, v94
	v_rcp_f32_e32 v95, v95
	v_rcp_f32_e32 v96, v96
	v_rcp_f32_e32 v97, v97
	v_rcp_f32_e32 v98, v98
	v_rcp_f32_e32 v99, v99
	v_rcp_f32_e32 v100, v100
	v_rcp_f32_e32 v101, v101
	v_rcp_f32_e32 v102, v102
	v_rcp_f32_e32 v103, v103
	v_rcp_f32_e32 v104, v104
	v_rcp_f32_e32 v105, v105
	v_rcp_f32_e32 v106, v106
	v_rcp_f32_e32 v107, v107
	v_mul_f32_e32 v92, v92, v248
	v_mul_f32_e32 v93, v93, v248
	v_mul_f32_e32 v94, v94, v248
	v_mul_f32_e32 v95, v95, v248
	v_mul_f32_e32 v96, v96, v249
	v_mul_f32_e32 v97, v97, v249
	v_mul_f32_e32 v98, v98, v249
	v_mul_f32_e32 v99, v99, v249
	v_add_f32_e32 v108, v92, v92
	v_add_f32_e32 v109, v93, v93
	v_add_f32_e32 v110, v94, v94
	v_add_f32_e32 v111, v95, v95
	v_add_f32_e32 v112, v96, v96
	v_add_f32_e32 v113, v97, v97
	v_add_f32_e32 v114, v98, v98
	v_add_f32_e32 v115, v99, v99
	v_cmp_ngt_f32_e64 s[60:61], s9, v108
	v_cmp_ngt_f32_e64 s[62:63], s9, v109
	v_cmp_ngt_f32_e64 s[64:65], s9, v110
	v_cmp_ngt_f32_e64 s[66:67], s9, v111
	v_cmp_ngt_f32_e64 s[68:69], s9, v112
	v_cmp_ngt_f32_e64 s[70:71], s9, v113
	v_cmp_ngt_f32_e64 s[72:73], s9, v114
	v_cmp_ngt_f32_e64 s[74:75], s9, v115
	v_fmamk_f32 v205, v108, 0x3ab60b61, v169
	v_fmamk_f32 v206, v109, 0x3ab60b61, v169
	v_fmamk_f32 v207, v110, 0x3ab60b61, v169
	v_fmamk_f32 v208, v111, 0x3ab60b61, v169
	v_fmamk_f32 v209, v112, 0x3ab60b61, v169
	v_fmamk_f32 v210, v113, 0x3ab60b61, v169
	v_fmamk_f32 v211, v114, 0x3ab60b61, v169
	v_fmamk_f32 v212, v115, 0x3ab60b61, v169
	v_fmaak_f32 v205, v108, v205, 0x3d2aaaab
	v_fmaak_f32 v206, v109, v206, 0x3d2aaaab
	v_fmaak_f32 v207, v110, v207, 0x3d2aaaab
	v_fmaak_f32 v208, v111, v208, 0x3d2aaaab
	v_fmaak_f32 v209, v112, v209, 0x3d2aaaab
	v_fmaak_f32 v210, v113, v210, 0x3d2aaaab
	v_fmaak_f32 v211, v114, v211, 0x3d2aaaab
	v_fmaak_f32 v212, v115, v212, 0x3d2aaaab
	v_fmaak_f32 v205, v108, v205, 0x3e2aaaab
	v_fmaak_f32 v206, v109, v206, 0x3e2aaaab
	v_fmaak_f32 v207, v110, v207, 0x3e2aaaab
	v_fmaak_f32 v208, v111, v208, 0x3e2aaaab
	v_fmaak_f32 v209, v112, v209, 0x3e2aaaab
	v_fmaak_f32 v210, v113, v210, 0x3e2aaaab
	v_fmaak_f32 v211, v114, v211, 0x3e2aaaab
	v_fmaak_f32 v212, v115, v212, 0x3e2aaaab
	v_fma_f32 v205, v108, v205, 0.5
	v_fma_f32 v206, v109, v206, 0.5
	v_fma_f32 v207, v110, v207, 0.5
	v_fma_f32 v208, v111, v208, 0.5
	v_fma_f32 v209, v112, v209, 0.5
	v_fma_f32 v210, v113, v210, 0.5
	v_fma_f32 v211, v114, v211, 0.5
	v_fma_f32 v212, v115, v212, 0.5
	v_fma_f32 v205, v108, v205, 1.0
	v_fma_f32 v206, v109, v206, 1.0
	v_fma_f32 v207, v110, v207, 1.0
	v_fma_f32 v208, v111, v208, 1.0
	v_fma_f32 v209, v112, v209, 1.0
	v_fma_f32 v210, v113, v210, 1.0
	v_fma_f32 v211, v114, v211, 1.0
	v_fma_f32 v212, v115, v212, 1.0
	v_mul_f32_e64 v205, v205, -v108
	v_mul_f32_e64 v206, v206, -v109
	v_mul_f32_e64 v207, v207, -v110
	v_mul_f32_e64 v208, v208, -v111
	v_mul_f32_e64 v209, v209, -v112
	v_mul_f32_e64 v210, v210, -v113
	v_mul_f32_e64 v211, v211, -v114
	v_mul_f32_e64 v212, v212, -v115
	v_mul_f32_e32 v189, 0x3fb8aa3b, v108
	v_mul_f32_e32 v190, 0x3fb8aa3b, v109
	v_mul_f32_e32 v191, 0x3fb8aa3b, v110
	v_mul_f32_e32 v192, 0x3fb8aa3b, v111
	v_mul_f32_e32 v193, 0x3fb8aa3b, v112
	v_mul_f32_e32 v194, 0x3fb8aa3b, v113
	v_mul_f32_e32 v195, 0x3fb8aa3b, v114
	v_mul_f32_e32 v196, 0x3fb8aa3b, v115
	v_exp_f32_e32 v189, v189
	v_exp_f32_e32 v190, v190
	v_exp_f32_e32 v191, v191
	v_exp_f32_e32 v192, v192
	v_exp_f32_e32 v193, v193
	v_exp_f32_e32 v194, v194
	v_exp_f32_e32 v195, v195
	v_exp_f32_e32 v196, v196
	v_sub_f32_e32 v189, 1.0, v189
	v_sub_f32_e32 v190, 1.0, v190
	v_sub_f32_e32 v191, 1.0, v191
	v_sub_f32_e32 v192, 1.0, v192
	v_sub_f32_e32 v193, 1.0, v193
	v_sub_f32_e32 v194, 1.0, v194
	v_sub_f32_e32 v195, 1.0, v195
	v_sub_f32_e32 v196, 1.0, v196
	v_cndmask_b32_e64 v189, v189, v205, s[60:61]
	v_cndmask_b32_e64 v190, v190, v206, s[62:63]
	v_cndmask_b32_e64 v191, v191, v207, s[64:65]
	v_cndmask_b32_e64 v192, v192, v208, s[66:67]
	v_cndmask_b32_e64 v193, v193, v209, s[68:69]
	v_cndmask_b32_e64 v194, v194, v210, s[70:71]
	v_cndmask_b32_e64 v195, v195, v211, s[72:73]
	v_cndmask_b32_e64 v196, v196, v212, s[74:75]
	v_max_f32_e32 v189, v189, v189
	v_max_f32_e32 v190, v190, v190
	v_max_f32_e32 v191, v191, v191
	v_max_f32_e32 v192, v192, v192
	v_max_f32_e32 v193, v193, v193
	v_max_f32_e32 v194, v194, v194
	v_max_f32_e32 v195, v195, v195
	v_max_f32_e32 v196, v196, v196
	v_max_f32_e32 v189, 0, v189
	v_max_f32_e32 v190, 0, v190
	v_max_f32_e32 v191, 0, v191
	v_max_f32_e32 v192, 0, v192
	v_max_f32_e32 v193, 0, v193
	v_max_f32_e32 v194, 0, v194
	v_max_f32_e32 v195, 0, v195
	v_max_f32_e32 v196, 0, v196
	v_sqrt_f32_e32 v189, v189
	v_sqrt_f32_e32 v190, v190
	v_sqrt_f32_e32 v191, v191
	v_sqrt_f32_e32 v192, v192
	v_sqrt_f32_e32 v193, v193
	v_sqrt_f32_e32 v194, v194
	v_sqrt_f32_e32 v195, v195
	v_sqrt_f32_e32 v196, v196
	s_waitcnt lgkmcnt(0)
;   __host__ __device__ __forceinline__ bf16_t* XC() const { return (bf16_t*)(wsl() + OFF_FFN); }
; __device__ __forceinline__ float bf2f(bf16_t h) { return __uint_as_float(((uint32_t)h) << 16); }
; __device__ __forceinline__ uint32_t pack2(float a, float b) { uint32_t r; asm("v_cvt_pk_bf16_f32 %0, %1, %2" : "=v"(r) : "v"(a), "v"(b)); return r; }
; __device__ __forceinline__ float sigmoidf_(float x) { return __builtin_amdgcn_rcpf(1.0f + __expf(-x)); }
; template <int EPI>
; __device__ __forceinline__ void gemm_tile(const Params& p, const EpiArgs& ea, const bf16_t* __restrict__ A, int lda,
;                                           const bf16_t* __restrict__ Bt, int K, int m0, int n0, char* smem) {
;     ...
;           float r = sigmoidf_(acc[mi][nh * 2][j] + ba);
;           float ig = sigmoidf_(acc[mi][nh * 2 + 1][j] + bx);
;           float la = r * sp8;
;           float x2 = 2.0f * la;
;           float poly = -x2 * (1.0f + x2 * (0.5f + x2 * (0.16666667f + x2 * (0.041666668f + x2 * (0.008333334f + x2 * 0.0013888889f)))));
;           float em = (x2 < -0.3f) ? (1.0f - __expf(x2)) : poly;
;           float u = bf2f(p.XC()[(size_t)(r0 + j) * D + ch]);
;           float inp = __builtin_amdgcn_sqrtf(fmaxf(em, 0.0f)) * (ig * u);
;           ea.outu[(size_t)(r0 + j) * D + ch] = pack2(la, inp);
	v_lshlrev_b32_e32 v197, 16, v197
	v_lshlrev_b32_e32 v198, 16, v198
	v_lshlrev_b32_e32 v199, 16, v199
	v_lshlrev_b32_e32 v200, 16, v200
	v_lshlrev_b32_e32 v201, 16, v201
	v_lshlrev_b32_e32 v202, 16, v202
	v_lshlrev_b32_e32 v203, 16, v203
	v_lshlrev_b32_e32 v204, 16, v204
	v_mul_f32_e32 v100, v100, v197
	v_mul_f32_e32 v101, v101, v198
	v_mul_f32_e32 v102, v102, v199
	v_mul_f32_e32 v103, v103, v200
	v_mul_f32_e32 v104, v104, v201
	v_mul_f32_e32 v105, v105, v202
	v_mul_f32_e32 v106, v106, v203
	v_mul_f32_e32 v107, v107, v204
	v_mul_f32_e32 v100, v189, v100
	v_mul_f32_e32 v101, v190, v101
	v_mul_f32_e32 v102, v191, v102
	v_mul_f32_e32 v103, v192, v103
	v_mul_f32_e32 v104, v193, v104
	v_mul_f32_e32 v105, v194, v105
	v_mul_f32_e32 v106, v195, v106
	v_mul_f32_e32 v107, v196, v107
	v_cvt_pk_bf16_f32 v100, v92, v100
	v_cvt_pk_bf16_f32 v101, v93, v101
	v_cvt_pk_bf16_f32 v102, v94, v102
	v_cvt_pk_bf16_f32 v103, v95, v103
	v_cvt_pk_bf16_f32 v104, v96, v104
	v_cvt_pk_bf16_f32 v105, v97, v105
	v_cvt_pk_bf16_f32 v106, v98, v106
	v_cvt_pk_bf16_f32 v107, v99, v107
	global_store_dword v236, v100, s[42:43]
	global_store_dword v237, v101, s[42:43]
	global_store_dword v238, v102, s[42:43]
	global_store_dword v239, v103, s[42:43]
	global_store_dword v236, v104, s[42:43] offset:64
	global_store_dword v237, v105, s[42:43] offset:64
	global_store_dword v238, v106, s[42:43] offset:64
	global_store_dword v239, v107, s[42:43] offset:64
	ds_read_u16 v197, v178 offset:4608
	ds_read_u16 v198, v178 offset:4752
	ds_read_u16 v199, v178 offset:4896
	ds_read_u16 v200, v178 offset:5040
	ds_read_u16 v201, v178 offset:4640
	ds_read_u16 v202, v178 offset:4784
	ds_read_u16 v203, v178 offset:4928
	ds_read_u16 v204, v178 offset:5072
	v_add_u32_e32 v236, 0x20000, v245
	v_add_u32_e32 v237, 0x21000, v245
	v_add_u32_e32 v238, 0x22000, v245
	v_add_u32_e32 v239, 0x23000, v245
	v_add_f32_e32 v92, v28, v250
	v_add_f32_e32 v93, v29, v250
	v_add_f32_e32 v94, v30, v250
	v_add_f32_e32 v95, v31, v250
	v_add_f32_e32 v96, v20, v246
	v_add_f32_e32 v97, v21, v246
	v_add_f32_e32 v98, v22, v246
	v_add_f32_e32 v99, v23, v246
	v_add_f32_e32 v100, v24, v251
	v_add_f32_e32 v101, v25, v251
	v_add_f32_e32 v102, v26, v251
	v_add_f32_e32 v103, v27, v251
	v_add_f32_e32 v104, v16, v247
	v_add_f32_e32 v105, v17, v247
	v_add_f32_e32 v106, v18, v247
	v_add_f32_e32 v107, v19, v247
	v_mul_f32_e32 v92, 0xbfb8aa3b, v92
	v_mul_f32_e32 v93, 0xbfb8aa3b, v93
	v_mul_f32_e32 v94, 0xbfb8aa3b, v94
	v_mul_f32_e32 v95, 0xbfb8aa3b, v95
	v_mul_f32_e32 v96, 0xbfb8aa3b, v96
	v_mul_f32_e32 v97, 0xbfb8aa3b, v97
	v_mul_f32_e32 v98, 0xbfb8aa3b, v98
	v_mul_f32_e32 v99, 0xbfb8aa3b, v99
	v_mul_f32_e32 v100, 0xbfb8aa3b, v100
	v_mul_f32_e32 v101, 0xbfb8aa3b, v101
	v_mul_f32_e32 v102, 0xbfb8aa3b, v102
	v_mul_f32_e32 v103, 0xbfb8aa3b, v103
	v_mul_f32_e32 v104, 0xbfb8aa3b, v104
	v_mul_f32_e32 v105, 0xbfb8aa3b, v105
	v_mul_f32_e32 v106, 0xbfb8aa3b, v106
	v_mul_f32_e32 v107, 0xbfb8aa3b, v107
	v_exp_f32_e32 v92, v92
	v_exp_f32_e32 v93, v93
	v_exp_f32_e32 v94, v94
	v_exp_f32_e32 v95, v95
	v_exp_f32_e32 v96, v96
	v_exp_f32_e32 v97, v97
	v_exp_f32_e32 v98, v98
	v_exp_f32_e32 v99, v99
	v_exp_f32_e32 v100, v100
	v_exp_f32_e32 v101, v101
	v_exp_f32_e32 v102, v102
	v_exp_f32_e32 v103, v103
	v_exp_f32_e32 v104, v104
	v_exp_f32_e32 v105, v105
	v_exp_f32_e32 v106, v106
	v_exp_f32_e32 v107, v107
	v_add_f32_e32 v92, 1.0, v92
	v_add_f32_e32 v93, 1.0, v93
	v_add_f32_e32 v94, 1.0, v94
	v_add_f32_e32 v95, 1.0, v95
	v_add_f32_e32 v96, 1.0, v96
	v_add_f32_e32 v97, 1.0, v97
	v_add_f32_e32 v98, 1.0, v98
	v_add_f32_e32 v99, 1.0, v99
	v_add_f32_e32 v100, 1.0, v100
	v_add_f32_e32 v101, 1.0, v101
	v_add_f32_e32 v102, 1.0, v102
	v_add_f32_e32 v103, 1.0, v103
	v_add_f32_e32 v104, 1.0, v104
	v_add_f32_e32 v105, 1.0, v105
	v_add_f32_e32 v106, 1.0, v106
	v_add_f32_e32 v107, 1.0, v107
	v_rcp_f32_e32 v92, v92
	v_rcp_f32_e32 v93, v93
	v_rcp_f32_e32 v94, v94
	v_rcp_f32_e32 v95, v95
	v_rcp_f32_e32 v96, v96
	v_rcp_f32_e32 v97, v97
	v_rcp_f32_e32 v98, v98
	v_rcp_f32_e32 v99, v99
	v_rcp_f32_e32 v100, v100
	v_rcp_f32_e32 v101, v101
	v_rcp_f32_e32 v102, v102
	v_rcp_f32_e32 v103, v103
	v_rcp_f32_e32 v104, v104
	v_rcp_f32_e32 v105, v105
	v_rcp_f32_e32 v106, v106
	v_rcp_f32_e32 v107, v107
	v_mul_f32_e32 v92, v92, v248
	v_mul_f32_e32 v93, v93, v248
	v_mul_f32_e32 v94, v94, v248
	v_mul_f32_e32 v95, v95, v248
	v_mul_f32_e32 v96, v96, v249
	v_mul_f32_e32 v97, v97, v249
	v_mul_f32_e32 v98, v98, v249
	v_mul_f32_e32 v99, v99, v249
	v_add_f32_e32 v108, v92, v92
	v_add_f32_e32 v109, v93, v93
	v_add_f32_e32 v110, v94, v94
	v_add_f32_e32 v111, v95, v95
	v_add_f32_e32 v112, v96, v96
	v_add_f32_e32 v113, v97, v97
	v_add_f32_e32 v114, v98, v98
	v_add_f32_e32 v115, v99, v99
	v_cmp_ngt_f32_e64 s[60:61], s9, v108
	v_cmp_ngt_f32_e64 s[62:63], s9, v109
	v_cmp_ngt_f32_e64 s[64:65], s9, v110
	v_cmp_ngt_f32_e64 s[66:67], s9, v111
	v_cmp_ngt_f32_e64 s[68:69], s9, v112
	v_cmp_ngt_f32_e64 s[70:71], s9, v113
	v_cmp_ngt_f32_e64 s[72:73], s9, v114
	v_cmp_ngt_f32_e64 s[74:75], s9, v115
	v_fmamk_f32 v205, v108, 0x3ab60b61, v169
	v_fmamk_f32 v206, v109, 0x3ab60b61, v169
	v_fmamk_f32 v207, v110, 0x3ab60b61, v169
	v_fmamk_f32 v208, v111, 0x3ab60b61, v169
	v_fmamk_f32 v209, v112, 0x3ab60b61, v169
	v_fmamk_f32 v210, v113, 0x3ab60b61, v169
	v_fmamk_f32 v211, v114, 0x3ab60b61, v169
	v_fmamk_f32 v212, v115, 0x3ab60b61, v169
	v_fmaak_f32 v205, v108, v205, 0x3d2aaaab
	v_fmaak_f32 v206, v109, v206, 0x3d2aaaab
	v_fmaak_f32 v207, v110, v207, 0x3d2aaaab
	v_fmaak_f32 v208, v111, v208, 0x3d2aaaab
	v_fmaak_f32 v209, v112, v209, 0x3d2aaaab
	v_fmaak_f32 v210, v113, v210, 0x3d2aaaab
	v_fmaak_f32 v211, v114, v211, 0x3d2aaaab
;   __host__ __device__ __forceinline__ bf16_t* XC() const { return (bf16_t*)(wsl() + OFF_FFN); }
; __device__ __forceinline__ float bf2f(bf16_t h) { return __uint_as_float(((uint32_t)h) << 16); }
; __device__ __forceinline__ uint32_t pack2(float a, float b) { uint32_t r; asm("v_cvt_pk_bf16_f32 %0, %1, %2" : "=v"(r) : "v"(a), "v"(b)); return r; }
; __device__ __forceinline__ float sigmoidf_(float x) { return __builtin_amdgcn_rcpf(1.0f + __expf(-x)); }
; template <int EPI>
; __device__ __forceinline__ void gemm_tile(const Params& p, const EpiArgs& ea, const bf16_t* __restrict__ A, int lda,
;                                           const bf16_t* __restrict__ Bt, int K, int m0, int n0, char* smem) {
;     ...
;           float r = sigmoidf_(acc[mi][nh * 2][j] + ba);
;           float ig = sigmoidf_(acc[mi][nh * 2 + 1][j] + bx);
;           float la = r * sp8;
;           float x2 = 2.0f * la;
;           float poly = -x2 * (1.0f + x2 * (0.5f + x2 * (0.16666667f + x2 * (0.041666668f + x2 * (0.008333334f + x2 * 0.0013888889f)))));
;           float em = (x2 < -0.3f) ? (1.0f - __expf(x2)) : poly;
;           float u = bf2f(p.XC()[(size_t)(r0 + j) * D + ch]);
;           float inp = __builtin_amdgcn_sqrtf(fmaxf(em, 0.0f)) * (ig * u);
;           ea.outu[(size_t)(r0 + j) * D + ch] = pack2(la, inp);
	v_fmaak_f32 v212, v115, v212, 0x3d2aaaab
	v_fmaak_f32 v205, v108, v205, 0x3e2aaaab
	v_fmaak_f32 v206, v109, v206, 0x3e2aaaab
	v_fmaak_f32 v207, v110, v207, 0x3e2aaaab
	v_fmaak_f32 v208, v111, v208, 0x3e2aaaab
	v_fmaak_f32 v209, v112, v209, 0x3e2aaaab
	v_fmaak_f32 v210, v113, v210, 0x3e2aaaab
	v_fmaak_f32 v211, v114, v211, 0x3e2aaaab
	v_fmaak_f32 v212, v115, v212, 0x3e2aaaab
	v_fma_f32 v205, v108, v205, 0.5
	v_fma_f32 v206, v109, v206, 0.5
	v_fma_f32 v207, v110, v207, 0.5
	v_fma_f32 v208, v111, v208, 0.5
	v_fma_f32 v209, v112, v209, 0.5
	v_fma_f32 v210, v113, v210, 0.5
	v_fma_f32 v211, v114, v211, 0.5
	v_fma_f32 v212, v115, v212, 0.5
	v_fma_f32 v205, v108, v205, 1.0
	v_fma_f32 v206, v109, v206, 1.0
	v_fma_f32 v207, v110, v207, 1.0
	v_fma_f32 v208, v111, v208, 1.0
	v_fma_f32 v209, v112, v209, 1.0
	v_fma_f32 v210, v113, v210, 1.0
	v_fma_f32 v211, v114, v211, 1.0
	v_fma_f32 v212, v115, v212, 1.0
	v_mul_f32_e64 v205, v205, -v108
	v_mul_f32_e64 v206, v206, -v109
	v_mul_f32_e64 v207, v207, -v110
	v_mul_f32_e64 v208, v208, -v111
	v_mul_f32_e64 v209, v209, -v112
	v_mul_f32_e64 v210, v210, -v113
	v_mul_f32_e64 v211, v211, -v114
	v_mul_f32_e64 v212, v212, -v115
	v_mul_f32_e32 v189, 0x3fb8aa3b, v108
	v_mul_f32_e32 v190, 0x3fb8aa3b, v109
	v_mul_f32_e32 v191, 0x3fb8aa3b, v110
	v_mul_f32_e32 v192, 0x3fb8aa3b, v111
	v_mul_f32_e32 v193, 0x3fb8aa3b, v112
	v_mul_f32_e32 v194, 0x3fb8aa3b, v113
	v_mul_f32_e32 v195, 0x3fb8aa3b, v114
	v_mul_f32_e32 v196, 0x3fb8aa3b, v115
	v_exp_f32_e32 v189, v189
	v_exp_f32_e32 v190, v190
	v_exp_f32_e32 v191, v191
	v_exp_f32_e32 v192, v192
	v_exp_f32_e32 v193, v193
	v_exp_f32_e32 v194, v194
	v_exp_f32_e32 v195, v195
	v_exp_f32_e32 v196, v196
	v_sub_f32_e32 v189, 1.0, v189
	v_sub_f32_e32 v190, 1.0, v190
	v_sub_f32_e32 v191, 1.0, v191
	v_sub_f32_e32 v192, 1.0, v192
	v_sub_f32_e32 v193, 1.0, v193
	v_sub_f32_e32 v194, 1.0, v194
	v_sub_f32_e32 v195, 1.0, v195
	v_sub_f32_e32 v196, 1.0, v196
	v_cndmask_b32_e64 v189, v189, v205, s[60:61]
	v_cndmask_b32_e64 v190, v190, v206, s[62:63]
	v_cndmask_b32_e64 v191, v191, v207, s[64:65]
	v_cndmask_b32_e64 v192, v192, v208, s[66:67]
	v_cndmask_b32_e64 v193, v193, v209, s[68:69]
	v_cndmask_b32_e64 v194, v194, v210, s[70:71]
	v_cndmask_b32_e64 v195, v195, v211, s[72:73]
	v_cndmask_b32_e64 v196, v196, v212, s[74:75]
	v_max_f32_e32 v189, v189, v189
	v_max_f32_e32 v190, v190, v190
	v_max_f32_e32 v191, v191, v191
	v_max_f32_e32 v192, v192, v192
	v_max_f32_e32 v193, v193, v193
	v_max_f32_e32 v194, v194, v194
	v_max_f32_e32 v195, v195, v195
	v_max_f32_e32 v196, v196, v196
	v_max_f32_e32 v189, 0, v189
	v_max_f32_e32 v190, 0, v190
	v_max_f32_e32 v191, 0, v191
	v_max_f32_e32 v192, 0, v192
	v_max_f32_e32 v193, 0, v193
	v_max_f32_e32 v194, 0, v194
	v_max_f32_e32 v195, 0, v195
	v_max_f32_e32 v196, 0, v196
	v_sqrt_f32_e32 v189, v189
	v_sqrt_f32_e32 v190, v190
	v_sqrt_f32_e32 v191, v191
	v_sqrt_f32_e32 v192, v192
	v_sqrt_f32_e32 v193, v193
	v_sqrt_f32_e32 v194, v194
	v_sqrt_f32_e32 v195, v195
	v_sqrt_f32_e32 v196, v196
	s_waitcnt lgkmcnt(0)
	v_lshlrev_b32_e32 v197, 16, v197
	v_lshlrev_b32_e32 v198, 16, v198
	v_lshlrev_b32_e32 v199, 16, v199
	v_lshlrev_b32_e32 v200, 16, v200
	v_lshlrev_b32_e32 v201, 16, v201
	v_lshlrev_b32_e32 v202, 16, v202
	v_lshlrev_b32_e32 v203, 16, v203
	v_lshlrev_b32_e32 v204, 16, v204
	v_mul_f32_e32 v100, v100, v197
	v_mul_f32_e32 v101, v101, v198
	v_mul_f32_e32 v102, v102, v199
	v_mul_f32_e32 v103, v103, v200
	v_mul_f32_e32 v104, v104, v201
	v_mul_f32_e32 v105, v105, v202
	v_mul_f32_e32 v106, v106, v203
	v_mul_f32_e32 v107, v107, v204
	v_mul_f32_e32 v100, v189, v100
	v_mul_f32_e32 v101, v190, v101
	v_mul_f32_e32 v102, v191, v102
	v_mul_f32_e32 v103, v192, v103
	v_mul_f32_e32 v104, v193, v104
	v_mul_f32_e32 v105, v194, v105
	v_mul_f32_e32 v106, v195, v106
	v_mul_f32_e32 v107, v196, v107
	v_cvt_pk_bf16_f32 v100, v92, v100
	v_cvt_pk_bf16_f32 v101, v93, v101
	v_cvt_pk_bf16_f32 v102, v94, v102
	v_cvt_pk_bf16_f32 v103, v95, v103
	v_cvt_pk_bf16_f32 v104, v96, v104
	v_cvt_pk_bf16_f32 v105, v97, v105
	v_cvt_pk_bf16_f32 v106, v98, v106
	v_cvt_pk_bf16_f32 v107, v99, v107
	global_store_dword v236, v100, s[42:43]
	global_store_dword v237, v101, s[42:43]
	global_store_dword v238, v102, s[42:43]
	global_store_dword v239, v103, s[42:43]
	global_store_dword v236, v104, s[42:43] offset:64
	global_store_dword v237, v105, s[42:43] offset:64
	global_store_dword v238, v106, s[42:43] offset:64
	global_store_dword v239, v107, s[42:43] offset:64
	ds_read_u16 v197, v178 offset:6912
	ds_read_u16 v198, v178 offset:7056
	ds_read_u16 v199, v178 offset:7200
	ds_read_u16 v200, v178 offset:7344
	ds_read_u16 v201, v178 offset:6944
	ds_read_u16 v202, v178 offset:7088
	ds_read_u16 v203, v178 offset:7232
	ds_read_u16 v204, v178 offset:7376
	v_add_u32_e32 v236, 0x30000, v245
	v_add_u32_e32 v237, 0x31000, v245
	v_add_u32_e32 v238, 0x32000, v245
	v_add_u32_e32 v239, 0x33000, v245
	v_add_f32_e32 v92, v12, v250
	v_add_f32_e32 v93, v13, v250
	v_add_f32_e32 v94, v14, v250
	v_add_f32_e32 v95, v15, v250
	v_add_f32_e32 v96, v4, v246
	v_add_f32_e32 v97, v5, v246
	v_add_f32_e32 v98, v6, v246
	v_add_f32_e32 v99, v7, v246
	v_add_f32_e32 v100, v8, v251
	v_add_f32_e32 v101, v9, v251
	v_add_f32_e32 v102, v10, v251
	v_add_f32_e32 v103, v11, v251
	v_add_f32_e32 v104, v0, v247
	v_add_f32_e32 v105, v1, v247
	v_add_f32_e32 v106, v2, v247
	v_add_f32_e32 v107, v3, v247
	v_mul_f32_e32 v92, 0xbfb8aa3b, v92
	v_mul_f32_e32 v93, 0xbfb8aa3b, v93
	v_mul_f32_e32 v94, 0xbfb8aa3b, v94
	v_mul_f32_e32 v95, 0xbfb8aa3b, v95
	v_mul_f32_e32 v96, 0xbfb8aa3b, v96
	v_mul_f32_e32 v97, 0xbfb8aa3b, v97
	v_mul_f32_e32 v98, 0xbfb8aa3b, v98
	v_mul_f32_e32 v99, 0xbfb8aa3b, v99
; __device__ __forceinline__ float sigmoidf_(float x) { return __builtin_amdgcn_rcpf(1.0f + __expf(-x)); }
; template <int EPI>
; __device__ __forceinline__ void gemm_tile(const Params& p, const EpiArgs& ea, const bf16_t* __restrict__ A, int lda,
;                                           const bf16_t* __restrict__ Bt, int K, int m0, int n0, char* smem) {
;     ...
;           float r = sigmoidf_(acc[mi][nh * 2][j] + ba);
;           float ig = sigmoidf_(acc[mi][nh * 2 + 1][j] + bx);
;           float la = r * sp8;
;           float x2 = 2.0f * la;
;           float poly = -x2 * (1.0f + x2 * (0.5f + x2 * (0.16666667f + x2 * (0.041666668f + x2 * (0.008333334f + x2 * 0.0013888889f)))));
;           float em = (x2 < -0.3f) ? (1.0f - __expf(x2)) : poly;
	v_mul_f32_e32 v100, 0xbfb8aa3b, v100
	v_mul_f32_e32 v101, 0xbfb8aa3b, v101
	v_mul_f32_e32 v102, 0xbfb8aa3b, v102
	v_mul_f32_e32 v103, 0xbfb8aa3b, v103
	v_mul_f32_e32 v104, 0xbfb8aa3b, v104
	v_mul_f32_e32 v105, 0xbfb8aa3b, v105
	v_mul_f32_e32 v106, 0xbfb8aa3b, v106
	v_mul_f32_e32 v107, 0xbfb8aa3b, v107
	v_exp_f32_e32 v92, v92
	v_exp_f32_e32 v93, v93
	v_exp_f32_e32 v94, v94
	v_exp_f32_e32 v95, v95
	v_exp_f32_e32 v96, v96
	v_exp_f32_e32 v97, v97
	v_exp_f32_e32 v98, v98
	v_exp_f32_e32 v99, v99
	v_exp_f32_e32 v100, v100
	v_exp_f32_e32 v101, v101
	v_exp_f32_e32 v102, v102
	v_exp_f32_e32 v103, v103
	v_exp_f32_e32 v104, v104
	v_exp_f32_e32 v105, v105
	v_exp_f32_e32 v106, v106
	v_exp_f32_e32 v107, v107
	v_add_f32_e32 v92, 1.0, v92
	v_add_f32_e32 v93, 1.0, v93
	v_add_f32_e32 v94, 1.0, v94
	v_add_f32_e32 v95, 1.0, v95
	v_add_f32_e32 v96, 1.0, v96
	v_add_f32_e32 v97, 1.0, v97
	v_add_f32_e32 v98, 1.0, v98
	v_add_f32_e32 v99, 1.0, v99
	v_add_f32_e32 v100, 1.0, v100
	v_add_f32_e32 v101, 1.0, v101
	v_add_f32_e32 v102, 1.0, v102
	v_add_f32_e32 v103, 1.0, v103
	v_add_f32_e32 v104, 1.0, v104
	v_add_f32_e32 v105, 1.0, v105
	v_add_f32_e32 v106, 1.0, v106
	v_add_f32_e32 v107, 1.0, v107
	v_rcp_f32_e32 v92, v92
	v_rcp_f32_e32 v93, v93
	v_rcp_f32_e32 v94, v94
	v_rcp_f32_e32 v95, v95
	v_rcp_f32_e32 v96, v96
	v_rcp_f32_e32 v97, v97
	v_rcp_f32_e32 v98, v98
	v_rcp_f32_e32 v99, v99
	v_rcp_f32_e32 v100, v100
	v_rcp_f32_e32 v101, v101
	v_rcp_f32_e32 v102, v102
	v_rcp_f32_e32 v103, v103
	v_rcp_f32_e32 v104, v104
	v_rcp_f32_e32 v105, v105
	v_rcp_f32_e32 v106, v106
	v_rcp_f32_e32 v107, v107
	v_mul_f32_e32 v92, v92, v248
	v_mul_f32_e32 v93, v93, v248
	v_mul_f32_e32 v94, v94, v248
	v_mul_f32_e32 v95, v95, v248
	v_mul_f32_e32 v96, v96, v249
	v_mul_f32_e32 v97, v97, v249
	v_mul_f32_e32 v98, v98, v249
	v_mul_f32_e32 v99, v99, v249
	v_add_f32_e32 v108, v92, v92
	v_add_f32_e32 v109, v93, v93
	v_add_f32_e32 v110, v94, v94
	v_add_f32_e32 v111, v95, v95
	v_add_f32_e32 v112, v96, v96
	v_add_f32_e32 v113, v97, v97
	v_add_f32_e32 v114, v98, v98
	v_add_f32_e32 v115, v99, v99
	v_cmp_ngt_f32_e64 s[60:61], s9, v108
	v_cmp_ngt_f32_e64 s[62:63], s9, v109
	v_cmp_ngt_f32_e64 s[64:65], s9, v110
	v_cmp_ngt_f32_e64 s[66:67], s9, v111
	v_cmp_ngt_f32_e64 s[68:69], s9, v112
	v_cmp_ngt_f32_e64 s[70:71], s9, v113
	v_cmp_ngt_f32_e64 s[72:73], s9, v114
	v_cmp_ngt_f32_e64 s[74:75], s9, v115
	v_fmamk_f32 v205, v108, 0x3ab60b61, v169
	v_fmamk_f32 v206, v109, 0x3ab60b61, v169
	v_fmamk_f32 v207, v110, 0x3ab60b61, v169
	v_fmamk_f32 v208, v111, 0x3ab60b61, v169
	v_fmamk_f32 v209, v112, 0x3ab60b61, v169
	v_fmamk_f32 v210, v113, 0x3ab60b61, v169
	v_fmamk_f32 v211, v114, 0x3ab60b61, v169
	v_fmamk_f32 v212, v115, 0x3ab60b61, v169
	v_fmaak_f32 v205, v108, v205, 0x3d2aaaab
	v_fmaak_f32 v206, v109, v206, 0x3d2aaaab
	v_fmaak_f32 v207, v110, v207, 0x3d2aaaab
	v_fmaak_f32 v208, v111, v208, 0x3d2aaaab
	v_fmaak_f32 v209, v112, v209, 0x3d2aaaab
	v_fmaak_f32 v210, v113, v210, 0x3d2aaaab
	v_fmaak_f32 v211, v114, v211, 0x3d2aaaab
	v_fmaak_f32 v212, v115, v212, 0x3d2aaaab
	v_fmaak_f32 v205, v108, v205, 0x3e2aaaab
	v_fmaak_f32 v206, v109, v206, 0x3e2aaaab
	v_fmaak_f32 v207, v110, v207, 0x3e2aaaab
	v_fmaak_f32 v208, v111, v208, 0x3e2aaaab
	v_fmaak_f32 v209, v112, v209, 0x3e2aaaab
	v_fmaak_f32 v210, v113, v210, 0x3e2aaaab
	v_fmaak_f32 v211, v114, v211, 0x3e2aaaab
	v_fmaak_f32 v212, v115, v212, 0x3e2aaaab
	v_fma_f32 v205, v108, v205, 0.5
	v_fma_f32 v206, v109, v206, 0.5
	v_fma_f32 v207, v110, v207, 0.5
	v_fma_f32 v208, v111, v208, 0.5
	v_fma_f32 v209, v112, v209, 0.5
	v_fma_f32 v210, v113, v210, 0.5
	v_fma_f32 v211, v114, v211, 0.5
	v_fma_f32 v212, v115, v212, 0.5
	v_fma_f32 v205, v108, v205, 1.0
	v_fma_f32 v206, v109, v206, 1.0
	v_fma_f32 v207, v110, v207, 1.0
	v_fma_f32 v208, v111, v208, 1.0
	v_fma_f32 v209, v112, v209, 1.0
	v_fma_f32 v210, v113, v210, 1.0
	v_fma_f32 v211, v114, v211, 1.0
	v_fma_f32 v212, v115, v212, 1.0
	v_mul_f32_e64 v205, v205, -v108
	v_mul_f32_e64 v206, v206, -v109
	v_mul_f32_e64 v207, v207, -v110
	v_mul_f32_e64 v208, v208, -v111
	v_mul_f32_e64 v209, v209, -v112
	v_mul_f32_e64 v210, v210, -v113
	v_mul_f32_e64 v211, v211, -v114
	v_mul_f32_e64 v212, v212, -v115
	v_mul_f32_e32 v189, 0x3fb8aa3b, v108
	v_mul_f32_e32 v190, 0x3fb8aa3b, v109
	v_mul_f32_e32 v191, 0x3fb8aa3b, v110
	v_mul_f32_e32 v192, 0x3fb8aa3b, v111
	v_mul_f32_e32 v193, 0x3fb8aa3b, v112
	v_mul_f32_e32 v194, 0x3fb8aa3b, v113
	v_mul_f32_e32 v195, 0x3fb8aa3b, v114
	v_mul_f32_e32 v196, 0x3fb8aa3b, v115
	v_exp_f32_e32 v189, v189
	v_exp_f32_e32 v190, v190
	v_exp_f32_e32 v191, v191
	v_exp_f32_e32 v192, v192
	v_exp_f32_e32 v193, v193
	v_exp_f32_e32 v194, v194
	v_exp_f32_e32 v195, v195
	v_exp_f32_e32 v196, v196
	v_sub_f32_e32 v189, 1.0, v189
	v_sub_f32_e32 v190, 1.0, v190
	v_sub_f32_e32 v191, 1.0, v191
	v_sub_f32_e32 v192, 1.0, v192
	v_sub_f32_e32 v193, 1.0, v193
	v_sub_f32_e32 v194, 1.0, v194
	v_sub_f32_e32 v195, 1.0, v195
	v_sub_f32_e32 v196, 1.0, v196
	v_cndmask_b32_e64 v189, v189, v205, s[60:61]
	v_cndmask_b32_e64 v190, v190, v206, s[62:63]
	v_cndmask_b32_e64 v191, v191, v207, s[64:65]
	v_cndmask_b32_e64 v192, v192, v208, s[66:67]
	v_cndmask_b32_e64 v193, v193, v209, s[68:69]
	v_cndmask_b32_e64 v194, v194, v210, s[70:71]
	v_cndmask_b32_e64 v195, v195, v211, s[72:73]
	v_cndmask_b32_e64 v196, v196, v212, s[74:75]
	v_max_f32_e32 v189, v189, v189
	v_max_f32_e32 v190, v190, v190
	v_max_f32_e32 v191, v191, v191
	v_max_f32_e32 v192, v192, v192
	v_max_f32_e32 v193, v193, v193
	v_max_f32_e32 v194, v194, v194
	v_max_f32_e32 v195, v195, v195
	v_max_f32_e32 v196, v196, v196
	v_max_f32_e32 v189, 0, v189
	v_max_f32_e32 v190, 0, v190
	v_max_f32_e32 v191, 0, v191
	v_max_f32_e32 v192, 0, v192
	v_max_f32_e32 v193, 0, v193
	v_max_f32_e32 v194, 0, v194
	v_max_f32_e32 v195, 0, v195
	v_max_f32_e32 v196, 0, v196
	v_sqrt_f32_e32 v189, v189
	v_sqrt_f32_e32 v190, v190
	v_sqrt_f32_e32 v191, v191
	v_sqrt_f32_e32 v192, v192
	v_sqrt_f32_e32 v193, v193
	v_sqrt_f32_e32 v194, v194
	v_sqrt_f32_e32 v195, v195
	v_sqrt_f32_e32 v196, v196
	s_waitcnt lgkmcnt(0)
;   __host__ __device__ __forceinline__ bf16_t* XC() const { return (bf16_t*)(wsl() + OFF_FFN); }
; __device__ __forceinline__ float bf2f(bf16_t h) { return __uint_as_float(((uint32_t)h) << 16); }
; __device__ __forceinline__ uint32_t pack2(float a, float b) { uint32_t r; asm("v_cvt_pk_bf16_f32 %0, %1, %2" : "=v"(r) : "v"(a), "v"(b)); return r; }
; template <int EPI>
; __device__ __forceinline__ void gemm_tile(const Params& p, const EpiArgs& ea, const bf16_t* __restrict__ A, int lda,
;                                           const bf16_t* __restrict__ Bt, int K, int m0, int n0, char* smem) {
;     ...
;           float u = bf2f(p.XC()[(size_t)(r0 + j) * D + ch]);
;           float inp = __builtin_amdgcn_sqrtf(fmaxf(em, 0.0f)) * (ig * u);
;           ea.outu[(size_t)(r0 + j) * D + ch] = pack2(la, inp);
	v_lshlrev_b32_e32 v197, 16, v197
	v_lshlrev_b32_e32 v198, 16, v198
	v_lshlrev_b32_e32 v199, 16, v199
	v_lshlrev_b32_e32 v200, 16, v200
	v_lshlrev_b32_e32 v201, 16, v201
	v_lshlrev_b32_e32 v202, 16, v202
	v_lshlrev_b32_e32 v203, 16, v203
	v_lshlrev_b32_e32 v204, 16, v204
	v_mul_f32_e32 v100, v100, v197
	v_mul_f32_e32 v101, v101, v198
	v_mul_f32_e32 v102, v102, v199
	v_mul_f32_e32 v103, v103, v200
	v_mul_f32_e32 v104, v104, v201
	v_mul_f32_e32 v105, v105, v202
	v_mul_f32_e32 v106, v106, v203
	v_mul_f32_e32 v107, v107, v204
	v_mul_f32_e32 v100, v189, v100
	v_mul_f32_e32 v101, v190, v101
	v_mul_f32_e32 v102, v191, v102
	v_mul_f32_e32 v103, v192, v103
	v_mul_f32_e32 v104, v193, v104
	v_mul_f32_e32 v105, v194, v105
	v_mul_f32_e32 v106, v195, v106
	v_mul_f32_e32 v107, v196, v107
	v_cvt_pk_bf16_f32 v100, v92, v100
	v_cvt_pk_bf16_f32 v101, v93, v101
	v_cvt_pk_bf16_f32 v102, v94, v102
	v_cvt_pk_bf16_f32 v103, v95, v103
	v_cvt_pk_bf16_f32 v104, v96, v104
	v_cvt_pk_bf16_f32 v105, v97, v105
	v_cvt_pk_bf16_f32 v106, v98, v106
	v_cvt_pk_bf16_f32 v107, v99, v107
	global_store_dword v236, v100, s[42:43]
	global_store_dword v237, v101, s[42:43]
	global_store_dword v238, v102, s[42:43]
	global_store_dword v239, v103, s[42:43]
	global_store_dword v236, v104, s[42:43] offset:64
	global_store_dword v237, v105, s[42:43] offset:64
	global_store_dword v238, v106, s[42:43] offset:64
	global_store_dword v239, v107, s[42:43] offset:64
	s_barrier
	s_mov_b32 s9, 0
